# adds rw_task<1> pipelined step loop on top of hand-written gd loader stage; gd/rw1/rw2 step loops all software-pipelined
# speedup vs baseline: 1.0177x; 1.0177x over previous
; #define LAS __attribute__((address_space(3)))
; template <int R>
; __device__ __forceinline__ void rw_task(const Params& p, LAS unsigned char* shm, const int tid, const int s, const int d, const int h, const int half) {
;     ...
;             for (int ti = 0; ti < ntiles; ++ti) {
;                 const LAS float* ib = inb + (ti & 1) * RW_INF; LAS float* ob = outb + (ti & 1) * RW_OUTF;
;                 LAS float* ow0 = j == 0 ? ob + row0 : outb + 2 * RW_OUTF + l; LAS float* ow1 = j == 0 ? ob + row1 : outb + 2 * RW_OUTF + 64 + l; const int omask = j == 0 ? -1 : 0;
; #pragma unroll 2
;                 for (int st = 0; st < TT; ++st) {
;                     const LAS float* sb = ib + st * RW_STRIDE;
;                     f32x2 ww[4], kk[4], bb[4], kc[4], wr[4];
;                     { const f32x4 a = *(const LAS f32x4*)(sb + 8 * j), b = *(const LAS f32x4*)(sb + 8 * j + 4); ww[0] = (f32x2){a[0], a[1]}; ww[1] = (f32x2){a[2], a[3]}; ww[2] = (f32x2){b[0], b[1]}; ww[3] = (f32x2){b[2], b[3]}; }
;                     { const f32x4 a = *(const LAS f32x4*)(sb + 64 + 8 * j), b = *(const LAS f32x4*)(sb + 64 + 8 * j + 4); kk[0] = (f32x2){a[0], a[1]}; kk[1] = (f32x2){a[2], a[3]}; kk[2] = (f32x2){b[0], b[1]}; kk[3] = (f32x2){b[2], b[3]}; }
;                     { const f32x4 a = *(const LAS f32x4*)(sb + 128 + 8 * j), b = *(const LAS f32x4*)(sb + 128 + 8 * j + 4); bb[0] = (f32x2){a[0], a[1]}; bb[1] = (f32x2){a[2], a[3]}; bb[2] = (f32x2){b[0], b[1]}; bb[3] = (f32x2){b[2], b[3]}; }
;                     { const f32x4 a = *(const LAS f32x4*)(sb + 192 + 8 * j), b = *(const LAS f32x4*)(sb + 192 + 8 * j + 4); kc[0] = (f32x2){a[0], a[1]}; kc[1] = (f32x2){a[2], a[3]}; kc[2] = (f32x2){b[0], b[1]}; kc[3] = (f32x2){b[2], b[3]}; }
;                     { const f32x4 a = *(const LAS f32x4*)(sb + 256 + 8 * j), b = *(const LAS f32x4*)(sb + 256 + 8 * j + 4); wr[0] = (f32x2){a[0], a[1]}; wr[1] = (f32x2){a[2], a[3]}; wr[2] = (f32x2){b[0], b[1]}; wr[3] = (f32x2){b[2], b[3]}; }
;                     const float v0 = sb[320 + row0], v1 = R == 2 ? sb[320 + row1] : 0.f; const f32x2 sc = *(const LAS f32x2*)(sb + 384); const float br = sc[0], kr = sc[1];
;                     if constexpr (R == 2) {
;                     f32x2 pa0 = s0[0] * kk[0], px0 = s0[0] * wr[0], pa1 = s1[0] * kk[0], px1 = s1[0] * wr[0];
; #pragma unroll
.LBB0_281:
	v_cndmask_b32_e64 v1, 0, 1, s[0:1]
	s_mov_b32 s4, 0xc200
	v_mul_lo_u32 v15, v1, s4
	s_and_b32 s4, s5, 1
	v_lshl_add_u32 v16, s4, 13, v10
	v_add_u32_e32 v1, 0, v15
	v_add_u32_e32 v14, v12, v15
	v_add_u32_e32 v15, v13, v15
	v_cndmask_b32_e32 v16, v11, v16, vcc
	s_mov_b32 s4, 64
	s_mov_b32 s6, 0
	v_mov_b32_e32 v126, v15
	v_mov_b32_e32 v127, v14
	v_mov_b32_e32 v128, v1
	v_mov_b32_e32 v129, v16
	s_mov_b32 s6, 0
	ds_read_b128 v[18:21], v126 offset:0
	ds_read_b128 v[22:25], v126 offset:16
	ds_read_b128 v[26:29], v126 offset:256
	ds_read_b128 v[30:33], v126 offset:272
	ds_read_b128 v[34:37], v126 offset:512
	ds_read_b128 v[38:41], v126 offset:528
	ds_read_b128 v[42:45], v126 offset:768
	ds_read_b128 v[46:49], v126 offset:784
	ds_read_b128 v[50:53], v126 offset:1024
	ds_read_b128 v[54:57], v126 offset:1040
	ds_read_b32 v58, v127 offset:0
	ds_read_b64 v[60:61], v128 offset:1536
	s_waitcnt lgkmcnt(3)
.Lrw1_step:
	ds_read_b128 v[64:67], v126 offset:1552
	ds_read_b128 v[68:71], v126 offset:1568
	ds_read_b128 v[72:75], v126 offset:1808
	ds_read_b128 v[76:79], v126 offset:1824
	ds_read_b128 v[80:83], v126 offset:2064
	ds_read_b128 v[84:87], v126 offset:2080
	ds_read_b128 v[92:95], v126 offset:2320
	ds_read_b128 v[96:99], v126 offset:2336
	ds_read_b128 v[100:103], v126 offset:2576
	ds_read_b128 v[104:107], v126 offset:2592
	ds_read_b32 v108, v127 offset:1552
	ds_read_b64 v[110:111], v128 offset:3088
	s_waitcnt lgkmcnt(12)
	v_pk_mul_f32 v[112:113], v[2:3], v[26:27]
	v_pk_mul_f32 v[114:115], v[2:3], v[50:51]
	v_pk_fma_f32 v[112:113], v[4:5], v[28:29], v[112:113]
	v_pk_fma_f32 v[114:115], v[4:5], v[52:53], v[114:115]
	v_pk_fma_f32 v[112:113], v[6:7], v[30:31], v[112:113]
	v_pk_fma_f32 v[114:115], v[6:7], v[54:55], v[114:115]
	v_pk_fma_f32 v[112:113], v[8:9], v[32:33], v[112:113]
	v_pk_fma_f32 v[114:115], v[8:9], v[56:57], v[114:115]
	v_pk_mul_f32 v[116:117], v[2:3], v[18:19]
	v_add_f32_e32 v112, v112, v113
	v_add_f32_e32 v114, v114, v115
	v_pk_mul_f32 v[118:119], v[4:5], v[20:21]
	v_pk_mul_f32 v[120:121], v[6:7], v[22:23]
	v_add_f32_dpp v112, v112, v112 quad_perm:[1,0,3,2] row_mask:0xf bank_mask:0xf bound_ctrl:1
	v_add_f32_dpp v114, v114, v114 quad_perm:[1,0,3,2] row_mask:0xf bank_mask:0xf bound_ctrl:1
	v_pk_mul_f32 v[122:123], v[8:9], v[24:25]
	v_pk_fma_f32 v[116:117], v[42:43], v[58:59], v[116:117] op_sel_hi:[1,0,1]
	v_add_f32_dpp v112, v112, v112 quad_perm:[2,3,0,1] row_mask:0xf bank_mask:0xf bound_ctrl:1
	v_add_f32_dpp v114, v114, v114 quad_perm:[2,3,0,1] row_mask:0xf bank_mask:0xf bound_ctrl:1
	v_pk_fma_f32 v[118:119], v[44:45], v[58:59], v[118:119] op_sel_hi:[1,0,1]
	v_pk_fma_f32 v[120:121], v[46:47], v[58:59], v[120:121] op_sel_hi:[1,0,1]
	v_add_f32_dpp v112, v112, v112 row_half_mirror row_mask:0xf bank_mask:0xf bound_ctrl:1
	v_add_f32_dpp v114, v114, v114 row_half_mirror row_mask:0xf bank_mask:0xf bound_ctrl:1
	v_pk_fma_f32 v[122:123], v[48:49], v[58:59], v[122:123] op_sel_hi:[1,0,1]
	v_mul_f32_e32 v124, v58, v61
	v_pk_fma_f32 v[2:3], v[34:35], v[112:113], v[116:117] op_sel_hi:[1,0,1] neg_lo:[0,1,0] neg_hi:[0,1,0]
	v_fma_f32 v124, -v112, v60, v124
	v_pk_fma_f32 v[4:5], v[36:37], v[112:113], v[118:119] op_sel_hi:[1,0,1] neg_lo:[0,1,0] neg_hi:[0,1,0]
	v_pk_fma_f32 v[6:7], v[38:39], v[112:113], v[120:121] op_sel_hi:[1,0,1] neg_lo:[0,1,0] neg_hi:[0,1,0]
	v_add_f32_e32 v125, v114, v124
	v_pk_fma_f32 v[8:9], v[40:41], v[112:113], v[122:123] op_sel_hi:[1,0,1] neg_lo:[0,1,0] neg_hi:[0,1,0]
	ds_write_b32 v129, v125 offset:0
	ds_read_b128 v[18:21], v126 offset:3104
	ds_read_b128 v[22:25], v126 offset:3120
	ds_read_b128 v[26:29], v126 offset:3360
	ds_read_b128 v[30:33], v126 offset:3376
	ds_read_b128 v[34:37], v126 offset:3616
	ds_read_b128 v[38:41], v126 offset:3632
	ds_read_b128 v[42:45], v126 offset:3872
	ds_read_b128 v[46:49], v126 offset:3888
	ds_read_b128 v[50:53], v126 offset:4128
	ds_read_b128 v[54:57], v126 offset:4144
	ds_read_b32 v58, v127 offset:3104
	ds_read_b64 v[60:61], v128 offset:4640
	s_waitcnt lgkmcnt(12)
	v_pk_mul_f32 v[112:113], v[2:3], v[72:73]
	v_pk_mul_f32 v[114:115], v[2:3], v[100:101]
	v_pk_fma_f32 v[112:113], v[4:5], v[74:75], v[112:113]
	v_pk_fma_f32 v[114:115], v[4:5], v[102:103], v[114:115]
	v_pk_fma_f32 v[112:113], v[6:7], v[76:77], v[112:113]
	v_pk_fma_f32 v[114:115], v[6:7], v[104:105], v[114:115]
	v_pk_fma_f32 v[112:113], v[8:9], v[78:79], v[112:113]
	v_pk_fma_f32 v[114:115], v[8:9], v[106:107], v[114:115]
	v_pk_mul_f32 v[116:117], v[2:3], v[64:65]
	v_add_f32_e32 v112, v112, v113
	v_add_f32_e32 v114, v114, v115
	v_pk_mul_f32 v[118:119], v[4:5], v[66:67]
	v_pk_mul_f32 v[120:121], v[6:7], v[68:69]
	v_add_f32_dpp v112, v112, v112 quad_perm:[1,0,3,2] row_mask:0xf bank_mask:0xf bound_ctrl:1
	v_add_f32_dpp v114, v114, v114 quad_perm:[1,0,3,2] row_mask:0xf bank_mask:0xf bound_ctrl:1
	v_pk_mul_f32 v[122:123], v[8:9], v[70:71]
	v_pk_fma_f32 v[116:117], v[92:93], v[108:109], v[116:117] op_sel_hi:[1,0,1]
	v_add_f32_dpp v112, v112, v112 quad_perm:[2,3,0,1] row_mask:0xf bank_mask:0xf bound_ctrl:1
	v_add_f32_dpp v114, v114, v114 quad_perm:[2,3,0,1] row_mask:0xf bank_mask:0xf bound_ctrl:1
	v_pk_fma_f32 v[118:119], v[94:95], v[108:109], v[118:119] op_sel_hi:[1,0,1]
	v_pk_fma_f32 v[120:121], v[96:97], v[108:109], v[120:121] op_sel_hi:[1,0,1]
	v_add_f32_dpp v112, v112, v112 row_half_mirror row_mask:0xf bank_mask:0xf bound_ctrl:1
	v_add_f32_dpp v114, v114, v114 row_half_mirror row_mask:0xf bank_mask:0xf bound_ctrl:1
	v_pk_fma_f32 v[122:123], v[98:99], v[108:109], v[122:123] op_sel_hi:[1,0,1]
	v_mul_f32_e32 v124, v108, v111
	v_pk_fma_f32 v[2:3], v[80:81], v[112:113], v[116:117] op_sel_hi:[1,0,1] neg_lo:[0,1,0] neg_hi:[0,1,0]
	v_fma_f32 v124, -v112, v110, v124
	v_pk_fma_f32 v[4:5], v[82:83], v[112:113], v[118:119] op_sel_hi:[1,0,1] neg_lo:[0,1,0] neg_hi:[0,1,0]
	v_pk_fma_f32 v[6:7], v[84:85], v[112:113], v[120:121] op_sel_hi:[1,0,1] neg_lo:[0,1,0] neg_hi:[0,1,0]
	v_add_f32_e32 v125, v114, v124
	v_pk_fma_f32 v[8:9], v[86:87], v[112:113], v[122:123] op_sel_hi:[1,0,1] neg_lo:[0,1,0] neg_hi:[0,1,0]
	ds_write_b32 v129, v125 offset:256
	ds_read_b128 v[64:67], v126 offset:4656
	ds_read_b128 v[68:71], v126 offset:4672
	ds_read_b128 v[72:75], v126 offset:4912
	ds_read_b128 v[76:79], v126 offset:4928
	ds_read_b128 v[80:83], v126 offset:5168
	ds_read_b128 v[84:87], v126 offset:5184
	ds_read_b128 v[92:95], v126 offset:5424
	ds_read_b128 v[96:99], v126 offset:5440
	ds_read_b128 v[100:103], v126 offset:5680
	ds_read_b128 v[104:107], v126 offset:5696
	ds_read_b32 v108, v127 offset:4656
	ds_read_b64 v[110:111], v128 offset:6192
	s_waitcnt lgkmcnt(12)
; #define LAS __attribute__((address_space(3)))
; template <int R>
; __device__ __forceinline__ void rw_task(const Params& p, LAS unsigned char* shm, const int tid, const int s, const int d, const int h, const int half) {
;     ...
;                 for (int st = 0; st < TT; ++st) {
;                     const LAS float* sb = ib + st * RW_STRIDE;
;                     f32x2 ww[4], kk[4], bb[4], kc[4], wr[4];
;                     { const f32x4 a = *(const LAS f32x4*)(sb + 8 * j), b = *(const LAS f32x4*)(sb + 8 * j + 4); ww[0] = (f32x2){a[0], a[1]}; ww[1] = (f32x2){a[2], a[3]}; ww[2] = (f32x2){b[0], b[1]}; ww[3] = (f32x2){b[2], b[3]}; }
;                     { const f32x4 a = *(const LAS f32x4*)(sb + 64 + 8 * j), b = *(const LAS f32x4*)(sb + 64 + 8 * j + 4); kk[0] = (f32x2){a[0], a[1]}; kk[1] = (f32x2){a[2], a[3]}; kk[2] = (f32x2){b[0], b[1]}; kk[3] = (f32x2){b[2], b[3]}; }
;                     { const f32x4 a = *(const LAS f32x4*)(sb + 128 + 8 * j), b = *(const LAS f32x4*)(sb + 128 + 8 * j + 4); bb[0] = (f32x2){a[0], a[1]}; bb[1] = (f32x2){a[2], a[3]}; bb[2] = (f32x2){b[0], b[1]}; bb[3] = (f32x2){b[2], b[3]}; }
;                     { const f32x4 a = *(const LAS f32x4*)(sb + 192 + 8 * j), b = *(const LAS f32x4*)(sb + 192 + 8 * j + 4); kc[0] = (f32x2){a[0], a[1]}; kc[1] = (f32x2){a[2], a[3]}; kc[2] = (f32x2){b[0], b[1]}; kc[3] = (f32x2){b[2], b[3]}; }
;                     { const f32x4 a = *(const LAS f32x4*)(sb + 256 + 8 * j), b = *(const LAS f32x4*)(sb + 256 + 8 * j + 4); wr[0] = (f32x2){a[0], a[1]}; wr[1] = (f32x2){a[2], a[3]}; wr[2] = (f32x2){b[0], b[1]}; wr[3] = (f32x2){b[2], b[3]}; }
;                     const float v0 = sb[320 + row0], v1 = R == 2 ? sb[320 + row1] : 0.f; const f32x2 sc = *(const LAS f32x2*)(sb + 384); const float br = sc[0], kr = sc[1];
;                     if constexpr (R == 2) {
;                     f32x2 pa0 = s0[0] * kk[0], px0 = s0[0] * wr[0], pa1 = s1[0] * kk[0], px1 = s1[0] * wr[0];
; #pragma unroll
;                     for (int e = 1; e < 4; ++e) { pa0 += s0[e] * kk[e]; px0 += s0[e] * wr[e]; pa1 += s1[e] * kk[e]; px1 += s1[e] * wr[e]; }
;                     const float sa0 = red8(pa0[0] + pa0[1]), x0 = red8(px0[0] + px0[1]), sa1 = red8(pa1[0] + pa1[1]), x1 = red8(px1[0] + px1[1]);
;                     const float o0 = x0 - sa0 * br + v0 * kr, o1 = x1 - sa1 * br + v1 * kr;
	v_pk_mul_f32 v[112:113], v[2:3], v[26:27]
	v_pk_mul_f32 v[114:115], v[2:3], v[50:51]
	v_pk_fma_f32 v[112:113], v[4:5], v[28:29], v[112:113]
	v_pk_fma_f32 v[114:115], v[4:5], v[52:53], v[114:115]
	v_pk_fma_f32 v[112:113], v[6:7], v[30:31], v[112:113]
	v_pk_fma_f32 v[114:115], v[6:7], v[54:55], v[114:115]
	v_pk_fma_f32 v[112:113], v[8:9], v[32:33], v[112:113]
	v_pk_fma_f32 v[114:115], v[8:9], v[56:57], v[114:115]
	v_pk_mul_f32 v[116:117], v[2:3], v[18:19]
	v_add_f32_e32 v112, v112, v113
	v_add_f32_e32 v114, v114, v115
	v_pk_mul_f32 v[118:119], v[4:5], v[20:21]
	v_pk_mul_f32 v[120:121], v[6:7], v[22:23]
	v_add_f32_dpp v112, v112, v112 quad_perm:[1,0,3,2] row_mask:0xf bank_mask:0xf bound_ctrl:1
	v_add_f32_dpp v114, v114, v114 quad_perm:[1,0,3,2] row_mask:0xf bank_mask:0xf bound_ctrl:1
	v_pk_mul_f32 v[122:123], v[8:9], v[24:25]
	v_pk_fma_f32 v[116:117], v[42:43], v[58:59], v[116:117] op_sel_hi:[1,0,1]
	v_add_f32_dpp v112, v112, v112 quad_perm:[2,3,0,1] row_mask:0xf bank_mask:0xf bound_ctrl:1
	v_add_f32_dpp v114, v114, v114 quad_perm:[2,3,0,1] row_mask:0xf bank_mask:0xf bound_ctrl:1
	v_pk_fma_f32 v[118:119], v[44:45], v[58:59], v[118:119] op_sel_hi:[1,0,1]
	v_pk_fma_f32 v[120:121], v[46:47], v[58:59], v[120:121] op_sel_hi:[1,0,1]
	v_add_f32_dpp v112, v112, v112 row_half_mirror row_mask:0xf bank_mask:0xf bound_ctrl:1
	v_add_f32_dpp v114, v114, v114 row_half_mirror row_mask:0xf bank_mask:0xf bound_ctrl:1
	v_pk_fma_f32 v[122:123], v[48:49], v[58:59], v[122:123] op_sel_hi:[1,0,1]
	v_mul_f32_e32 v124, v58, v61
	v_pk_fma_f32 v[2:3], v[34:35], v[112:113], v[116:117] op_sel_hi:[1,0,1] neg_lo:[0,1,0] neg_hi:[0,1,0]
	v_fma_f32 v124, -v112, v60, v124
	v_pk_fma_f32 v[4:5], v[36:37], v[112:113], v[118:119] op_sel_hi:[1,0,1] neg_lo:[0,1,0] neg_hi:[0,1,0]
	v_pk_fma_f32 v[6:7], v[38:39], v[112:113], v[120:121] op_sel_hi:[1,0,1] neg_lo:[0,1,0] neg_hi:[0,1,0]
	v_add_f32_e32 v125, v114, v124
	v_pk_fma_f32 v[8:9], v[40:41], v[112:113], v[122:123] op_sel_hi:[1,0,1] neg_lo:[0,1,0] neg_hi:[0,1,0]
	ds_write_b32 v129, v125 offset:512
	ds_read_b128 v[18:21], v126 offset:6208
	ds_read_b128 v[22:25], v126 offset:6224
	ds_read_b128 v[26:29], v126 offset:6464
	ds_read_b128 v[30:33], v126 offset:6480
	ds_read_b128 v[34:37], v126 offset:6720
	ds_read_b128 v[38:41], v126 offset:6736
	ds_read_b128 v[42:45], v126 offset:6976
	ds_read_b128 v[46:49], v126 offset:6992
	ds_read_b128 v[50:53], v126 offset:7232
	ds_read_b128 v[54:57], v126 offset:7248
	ds_read_b32 v58, v127 offset:6208
	ds_read_b64 v[60:61], v128 offset:7744
	s_waitcnt lgkmcnt(12)
	v_pk_mul_f32 v[112:113], v[2:3], v[72:73]
	v_pk_mul_f32 v[114:115], v[2:3], v[100:101]
	v_pk_fma_f32 v[112:113], v[4:5], v[74:75], v[112:113]
	v_pk_fma_f32 v[114:115], v[4:5], v[102:103], v[114:115]
	v_pk_fma_f32 v[112:113], v[6:7], v[76:77], v[112:113]
	v_pk_fma_f32 v[114:115], v[6:7], v[104:105], v[114:115]
	v_pk_fma_f32 v[112:113], v[8:9], v[78:79], v[112:113]
	v_pk_fma_f32 v[114:115], v[8:9], v[106:107], v[114:115]
	v_pk_mul_f32 v[116:117], v[2:3], v[64:65]
	v_add_f32_e32 v112, v112, v113
	v_add_f32_e32 v114, v114, v115
	v_pk_mul_f32 v[118:119], v[4:5], v[66:67]
	v_pk_mul_f32 v[120:121], v[6:7], v[68:69]
	v_add_f32_dpp v112, v112, v112 quad_perm:[1,0,3,2] row_mask:0xf bank_mask:0xf bound_ctrl:1
	v_add_f32_dpp v114, v114, v114 quad_perm:[1,0,3,2] row_mask:0xf bank_mask:0xf bound_ctrl:1
	v_pk_mul_f32 v[122:123], v[8:9], v[70:71]
	v_pk_fma_f32 v[116:117], v[92:93], v[108:109], v[116:117] op_sel_hi:[1,0,1]
	v_add_f32_dpp v112, v112, v112 quad_perm:[2,3,0,1] row_mask:0xf bank_mask:0xf bound_ctrl:1
	v_add_f32_dpp v114, v114, v114 quad_perm:[2,3,0,1] row_mask:0xf bank_mask:0xf bound_ctrl:1
	v_pk_fma_f32 v[118:119], v[94:95], v[108:109], v[118:119] op_sel_hi:[1,0,1]
	v_pk_fma_f32 v[120:121], v[96:97], v[108:109], v[120:121] op_sel_hi:[1,0,1]
	v_add_f32_dpp v112, v112, v112 row_half_mirror row_mask:0xf bank_mask:0xf bound_ctrl:1
	v_add_f32_dpp v114, v114, v114 row_half_mirror row_mask:0xf bank_mask:0xf bound_ctrl:1
	v_pk_fma_f32 v[122:123], v[98:99], v[108:109], v[122:123] op_sel_hi:[1,0,1]
	v_mul_f32_e32 v124, v108, v111
	v_pk_fma_f32 v[2:3], v[80:81], v[112:113], v[116:117] op_sel_hi:[1,0,1] neg_lo:[0,1,0] neg_hi:[0,1,0]
	v_fma_f32 v124, -v112, v110, v124
	v_pk_fma_f32 v[4:5], v[82:83], v[112:113], v[118:119] op_sel_hi:[1,0,1] neg_lo:[0,1,0] neg_hi:[0,1,0]
	v_pk_fma_f32 v[6:7], v[84:85], v[112:113], v[120:121] op_sel_hi:[1,0,1] neg_lo:[0,1,0] neg_hi:[0,1,0]
	v_add_f32_e32 v125, v114, v124
	v_pk_fma_f32 v[8:9], v[86:87], v[112:113], v[122:123] op_sel_hi:[1,0,1] neg_lo:[0,1,0] neg_hi:[0,1,0]
	ds_write_b32 v129, v125 offset:768
	v_add_u32_e32 v126, 0x1840, v126
	v_add_u32_e32 v127, 0x1840, v127
	v_add_u32_e32 v128, 0x1840, v128
	v_add_u32_e32 v129, 0x400, v129
	s_add_i32 s6, s6, 1
	s_cmp_eq_u32 s6, 8
	s_cbranch_scc0 .Lrw1_step
	s_add_i32 s5, s5, 1
	s_xor_b64 s[0:1], s[0:1], -1
	s_cmpk_eq_i32 s5, 0x200
	s_waitcnt lgkmcnt(0)
	s_barrier
	s_cbranch_scc0 .LBB0_281
